# dn_scan step: LDS reads hoisted above the prefetch, Q.s MFMA moved into stage 1, single loop body for all 68 steps
# baseline (speedup 1.0000x reference)
.LBB0_1378:
	s_barrier
	s_waitcnt vmcnt(7)
	ds_write_b128 v100, v[4:7]
	s_waitcnt vmcnt(6)
	ds_write_b128 v100, v[8:11] offset:9216
	s_waitcnt vmcnt(5)
	ds_write_b128 v100, v[24:27] offset:18432
	s_waitcnt vmcnt(4)
	ds_write_b16 v99, v12 offset:27648
	ds_write_b16_d16_hi v99, v12 offset:27792
	ds_write_b16 v99, v13 offset:27936
	ds_write_b16_d16_hi v99, v13 offset:28080
	ds_write_b16 v99, v14 offset:28224
	ds_write_b16_d16_hi v99, v14 offset:28368
	ds_write_b16 v99, v15 offset:28512
	ds_write_b16_d16_hi v99, v15 offset:28656
	s_waitcnt vmcnt(3)
	ds_write_b128 v98, v[16:19]
	s_waitcnt vmcnt(2)
	ds_write_b128 v98, v[20:23] offset:9216
	s_waitcnt vmcnt(1)
	ds_write_b128 v98, v[32:35] offset:18432
	s_waitcnt vmcnt(0)
	ds_write_b16 v97, v28 offset:27648
	ds_write_b16_d16_hi v97, v28 offset:27792
	ds_write_b16 v97, v29 offset:27936
	ds_write_b16_d16_hi v97, v29 offset:28080
	ds_write_b16 v97, v30 offset:28224
	ds_write_b16_d16_hi v97, v30 offset:28368
	ds_write_b16 v97, v31 offset:28512
	ds_write_b16_d16_hi v97, v31 offset:28656
	s_and_saveexec_b64 s[10:11], s[4:5]
	ds_write_b128 v96, v[0:3] offset:36864
	s_or_b64 exec, exec, s[10:11]
	s_and_saveexec_b64 s[10:11], s[6:7]
	ds_write_b32 v95, v94 offset:46848
	s_or_b64 exec, exec, s[10:11]
	v_cvt_pk_bf16_f32 v4, v66, v67
	v_cvt_pk_bf16_f32 v5, v68, v69
	ds_write_b64 v86, v[4:5] offset:39936
	s_waitcnt lgkmcnt(0)
	s_barrier
	v_mov_b32_e32 v102, s33
	v_add_u32_e32 v65, 0xb704, v79
	ds_read_b128 v[36:39], v82
	ds_read_b128 v[40:43], v83 offset:39936
	ds_read_b128 v[44:47], v82 offset:64
	ds_read_b128 v[48:51], v83 offset:40000
	ds_read_b32 v101, v102 offset:47100
	ds_read_b32 v208, v84 offset:46848
	ds_read2_b32 v[210:211], v65 offset1:1
	ds_read_b32 v209, v79 offset:46860
	ds_read_u16 v212, v93 offset:36864
	ds_read_u16 v213, v92 offset:36864
	ds_read_u16 v214, v89 offset:36864
	ds_read_u16 v215, v87 offset:36864
	s_cmp_gt_i32 s19, 63
	s_cbranch_scc1 .Lscan_skip
	s_add_i32 s10, s19, 3
	s_cmp_gt_u32 s10, 2
	s_mov_b64 s[10:11], -1
	s_cbranch_scc0 .LBB0_1384
	s_and_b64 s[10:11], s[2:3], exec
	s_cselect_b32 s13, s19, s17
	s_mov_b64 s[10:11], 0

.Lscan_skip:
	s_add_i32 s17, s17, -1
	s_add_i32 s19, s19, 1
	s_add_u32 s8, s8, 0x2000
	s_addc_u32 s9, s9, 0
	v_lshl_add_u64 v[72:73], v[72:73], 0, s[88:89]
	s_waitcnt lgkmcnt(8)
	v_mfma_f32_16x16x32_bf16 v[36:39], v[36:39], v[40:43], 0
	v_mfma_f32_16x16x32_bf16 v[36:39], v[44:47], v[48:51], v[36:39]
	ds_read_b128 v[216:219], v82 offset:18432
	ds_read_b128 v[220:223], v82 offset:18496
	ds_read_b128 v[224:227], v82 offset:9216
	ds_read_b128 v[228:231], v82 offset:9280
	ds_read_b128 v[232:235], v82 offset:27648
	ds_read_b128 v[236:239], v82 offset:27712
	s_waitcnt lgkmcnt(6)
	v_sub_f32_e32 v52, v101, v208
	v_sub_f32_e32 v53, v101, v210
	v_sub_f32_e32 v54, v101, v211
	v_sub_f32_e32 v55, v101, v209
	v_mul_f32_e32 v52, 0x3fb8aa3b, v52
	v_mul_f32_e32 v53, 0x3fb8aa3b, v53
	v_mul_f32_e32 v54, 0x3fb8aa3b, v54
	v_mul_f32_e32 v55, 0x3fb8aa3b, v55
	v_exp_f32_e32 v52, v52
	v_exp_f32_e32 v53, v53
	v_exp_f32_e32 v54, v54
	v_exp_f32_e32 v55, v55
	v_lshlrev_b32_e32 v212, 16, v212
	v_lshlrev_b32_e32 v213, 16, v213
	v_lshlrev_b32_e32 v214, 16, v214
	v_lshlrev_b32_e32 v215, 16, v215
	s_waitcnt lgkmcnt(4)
	v_mfma_f32_16x16x32_bf16 v[108:111], v[216:219], v[40:43], 0
	v_mfma_f32_16x16x32_bf16 v[108:111], v[220:223], v[48:51], v[108:111]
	v_pk_add_f32 v[36:37], v[212:213], v[36:37] neg_lo:[0,1] neg_hi:[0,1]
	v_pk_add_f32 v[38:39], v[214:215], v[38:39] neg_lo:[0,1] neg_hi:[0,1]
	v_pk_mul_f32 v[56:57], v[36:37], v[52:53]
	v_pk_mul_f32 v[58:59], v[38:39], v[54:55]
	v_cvt_pk_bf16_f32 v102, v36, v37
	v_cvt_pk_bf16_f32 v103, v38, v39
	ds_write_b64 v86, v[102:103] offset:42240
	v_cvt_pk_bf16_f32 v56, v56, v57
	v_cvt_pk_bf16_f32 v57, v58, v59
	ds_write_b64 v86, v[56:57] offset:44544
	v_mul_f32_e32 v212, 0x3fb8aa3b, v208
	v_mul_f32_e32 v213, 0x3fb8aa3b, v210
	v_mul_f32_e32 v214, 0x3fb8aa3b, v211
	v_mul_f32_e32 v215, 0x3fb8aa3b, v209
	v_mul_f32_e32 v248, 0x3fb8aa3b, v101
	v_exp_f32_e32 v212, v212
	v_exp_f32_e32 v213, v213
	v_exp_f32_e32 v214, v214
	v_exp_f32_e32 v215, v215
	v_exp_f32_e32 v248, v248
	s_waitcnt lgkmcnt(0)
	s_barrier
	ds_read_b128 v[52:55], v83 offset:42240
	ds_read_b128 v[56:59], v83 offset:42304
	ds_read_b128 v[240:243], v83 offset:44544
	ds_read_b128 v[244:247], v83 offset:44608
	v_add_u32_e32 v44, s15, v85
	v_ashrrev_i32_e32 v45, 31, v44
	v_lshlrev_b64 v[44:45], 9, v[44:45]
	v_lshl_add_u64 v[44:45], v[60:61], 0, v[44:45]
	v_add_u32_e32 v46, s15, v81
	v_ashrrev_i32_e32 v47, 31, v46
	v_lshlrev_b64 v[46:47], 9, v[46:47]
	v_lshl_add_u64 v[46:47], v[60:61], 0, v[46:47]
	v_add_u32_e32 v48, s15, v80
	v_ashrrev_i32_e32 v49, 31, v48
	v_lshlrev_b64 v[48:49], 9, v[48:49]
	v_lshl_add_u64 v[48:49], v[60:61], 0, v[48:49]
	v_add_u32_e32 v50, s15, v78
	v_ashrrev_i32_e32 v51, 31, v50
	v_lshlrev_b64 v[50:51], 9, v[50:51]
	v_lshl_add_u64 v[50:51], v[60:61], 0, v[50:51]
	s_waitcnt lgkmcnt(3)
	v_mfma_f32_16x16x32_bf16 v[224:227], v[224:227], v[52:55], 0
	s_waitcnt lgkmcnt(2)
	v_mfma_f32_16x16x32_bf16 v[224:227], v[228:231], v[56:59], v[224:227]
	s_waitcnt lgkmcnt(1)
	v_mfma_f32_16x16x32_bf16 v[232:235], v[232:235], v[240:243], 0
	s_waitcnt lgkmcnt(0)
	v_mfma_f32_16x16x32_bf16 v[232:235], v[236:239], v[244:247], v[232:235]
	s_nop 4
	v_fma_f32 v40, v108, v212, v224
	v_fma_f32 v41, v109, v213, v225
	v_fma_f32 v42, v110, v214, v226
	v_fma_f32 v43, v111, v215, v227
	v_bfe_u32 v52, v40, 16, 1
	v_bfe_u32 v53, v41, 16, 1
	v_bfe_u32 v54, v42, 16, 1
	v_bfe_u32 v55, v43, 16, 1
	v_add3_u32 v40, v40, v52, s42
	v_add3_u32 v41, v41, v53, s42
	v_add3_u32 v42, v42, v54, s42
	v_add3_u32 v43, v43, v55, s42
	global_store_short_d16_hi v[44:45], v40, off
	global_store_short_d16_hi v[46:47], v41, off
	global_store_short_d16_hi v[48:49], v42, off
	global_store_short_d16_hi v[50:51], v43, off
	v_pk_fma_f32 v[68:69], v[68:69], v[248:249], v[234:235] op_sel_hi:[1,0,1]
	v_pk_fma_f32 v[66:67], v[66:67], v[248:249], v[232:233] op_sel_hi:[1,0,1]
	s_cmp_lg_u32 s8, 0x88000
	s_cbranch_scc0 .Lscan_done
	s_mov_b32 s15, s13
	s_branch .LBB0_1378
